# mixer A: T5 bias preloaded into the QK accumulators (table stored / QK_C), scores = QK_C*acc with no LDS reads; K-fragment reads five deep, k-step outermost
# speedup vs baseline: 1.0091x; 1.0066x over previous
; __device__ __forceinline__ void attnA_unit(LAS unsigned char* lds, const Args& A, int unit) {
;     ...
;     for (int e = tid; e < 3 * 192; e += 512) { const int g = e / 192, idx = e % 192 - 32;
;         biasl[e] = (idx >= 0 && idx <= 128) ? ((const float*)(A.ws + WS_BIAS))[(g * 8 + h) * 132 + idx] : -1e30f; }
.LBB0_280:
	s_or_b64 exec, exec, s[8:9]
	v_add_u32_e32 v2, 0x200, v1
	v_cmp_lt_i32_e32 vcc, 63, v1
	s_waitcnt vmcnt(0)
	v_mul_f32_e32 v3, 0x40b17218, v3
	ds_write_b32 v0, v3
	v_add_u32_e32 v0, 0x800, v0
	s_or_b64 s[6:7], vcc, s[6:7]
	v_mov_b32_e32 v1, v2
	s_andn2_b64 exec, exec, s[6:7]
	s_cbranch_execz .LBB0_283

; #define LAS __attribute__((address_space(3)))
; #define MFMA32(a, b, c) __builtin_amdgcn_mfma_f32_32x32x16_bf16((a), (b), (c), 0, 0, 0)
; __device__ __forceinline__ void attnA_unit(LAS unsigned char* lds, const Args& A, int unit) {
;     ...
;                 f32x16 S[5];
; #pragma unroll
;                 for (int kt = 0; kt < 5; ++kt)
; #pragma unroll
;                     for (int i = 0; i < 16; ++i) S[kt][i] = 0.f;
; #pragma unroll
;                 for (int s = 0; s < 4; ++s)
; #pragma unroll
;                     for (int kt = 0; kt < 5; ++kt) S[kt] = MFMA32(*(const LAS bf16x8*)(kt_l + (rb + 32 * kt + ql) * AST + hh * 16 + 32 * s), qf[s], S[kt]);
.LBB0_295:
	v_add_u32_e32 v0, v163, v144
	v_mad_u64_u32 v[170:171], s[22:23], v0, s88, v[148:149]
	s_andn2_b64 vcc, exec, s[82:83]
	ds_read_b128 v[166:169], v170 offset:4096
	ds_read2_b32 v[64:65], v157 offset0:32 offset1:33
	ds_read2_b32 v[66:67], v157 offset0:34 offset1:35
	ds_read2_b32 v[68:69], v157 offset0:40 offset1:41
	ds_read2_b32 v[70:71], v157 offset0:42 offset1:43
	ds_read2_b32 v[72:73], v157 offset0:48 offset1:49
	ds_read2_b32 v[74:75], v157 offset0:50 offset1:51
	ds_read2_b32 v[76:77], v157 offset0:56 offset1:57
	ds_read2_b32 v[78:79], v157 offset0:58 offset1:59
	ds_read_b128 v[172:175], v170 offset:8704
	ds_read2_b32 v[48:49], v157 offset0:64 offset1:65
	ds_read2_b32 v[50:51], v157 offset0:66 offset1:67
	ds_read2_b32 v[52:53], v157 offset0:72 offset1:73
	ds_read2_b32 v[54:55], v157 offset0:74 offset1:75
	ds_read2_b32 v[56:57], v157 offset0:80 offset1:81
	ds_read2_b32 v[58:59], v157 offset0:82 offset1:83
	ds_read2_b32 v[60:61], v157 offset0:88 offset1:89
	ds_read2_b32 v[62:63], v157 offset0:90 offset1:91
	s_waitcnt vmcnt(15) lgkmcnt(9)
	v_mfma_f32_32x32x16_bf16 v[64:79], v[166:169], v[80:83], v[64:79]
	ds_read_b128 v[242:245], v170 offset:13312
	ds_read2_b32 v[32:33], v157 offset0:96 offset1:97
	ds_read2_b32 v[34:35], v157 offset0:98 offset1:99
	ds_read2_b32 v[36:37], v157 offset0:104 offset1:105
	ds_read2_b32 v[38:39], v157 offset0:106 offset1:107
	ds_read2_b32 v[40:41], v157 offset0:112 offset1:113
	ds_read2_b32 v[42:43], v157 offset0:114 offset1:115
	ds_read2_b32 v[44:45], v157 offset0:120 offset1:121
	ds_read2_b32 v[46:47], v157 offset0:122 offset1:123
	ds_read_b128 v[166:169], v170 offset:4128
	s_waitcnt lgkmcnt(10)
	v_mfma_f32_32x32x16_bf16 v[48:63], v[172:175], v[80:83], v[48:63]
	ds_read_b128 v[186:189], v170 offset:17920
	ds_read2_b32 v[16:17], v157 offset0:128 offset1:129
	ds_read2_b32 v[18:19], v157 offset0:130 offset1:131
	ds_read2_b32 v[20:21], v157 offset0:136 offset1:137
	ds_read2_b32 v[22:23], v157 offset0:138 offset1:139
	ds_read2_b32 v[24:25], v157 offset0:144 offset1:145
	ds_read2_b32 v[26:27], v157 offset0:146 offset1:147
	ds_read2_b32 v[28:29], v157 offset0:152 offset1:153
	ds_read2_b32 v[30:31], v157 offset0:154 offset1:155
	ds_read_b128 v[172:175], v170 offset:8736
	s_waitcnt lgkmcnt(11)
	v_mfma_f32_32x32x16_bf16 v[32:47], v[242:245], v[80:83], v[32:47]
	ds_read_b128 v[248:251], v170 offset:22528
	ds_read2_b32 v[0:1], v157 offset0:160 offset1:161
	ds_read2_b32 v[2:3], v157 offset0:162 offset1:163
	ds_read2_b32 v[4:5], v157 offset0:168 offset1:169
	ds_read2_b32 v[6:7], v157 offset0:170 offset1:171
	ds_read2_b32 v[8:9], v157 offset0:176 offset1:177
	ds_read2_b32 v[10:11], v157 offset0:178 offset1:179
	ds_read2_b32 v[12:13], v157 offset0:184 offset1:185
	ds_read2_b32 v[14:15], v157 offset0:186 offset1:187
	ds_read_b128 v[242:245], v170 offset:13344
	s_waitcnt lgkmcnt(11)
	v_mfma_f32_32x32x16_bf16 v[16:31], v[186:189], v[80:83], v[16:31]
	ds_read_b128 v[186:189], v170 offset:17952
	s_waitcnt lgkmcnt(2)
	v_mfma_f32_32x32x16_bf16 v[0:15], v[248:251], v[80:83], v[0:15]
	ds_read_b128 v[248:251], v170 offset:22560
	s_waitcnt vmcnt(14) lgkmcnt(4)
	v_mfma_f32_32x32x16_bf16 v[64:79], v[166:169], v[84:87], v[64:79]
	ds_read_b128 v[166:169], v170 offset:4160
	s_waitcnt lgkmcnt(4)
	v_mfma_f32_32x32x16_bf16 v[48:63], v[172:175], v[84:87], v[48:63]
	ds_read_b128 v[172:175], v170 offset:8768
	s_waitcnt lgkmcnt(4)
	v_mfma_f32_32x32x16_bf16 v[32:47], v[242:245], v[84:87], v[32:47]
	ds_read_b128 v[242:245], v170 offset:13376
	s_waitcnt lgkmcnt(4)
	v_mfma_f32_32x32x16_bf16 v[16:31], v[186:189], v[84:87], v[16:31]
	ds_read_b128 v[186:189], v170 offset:17984
	s_waitcnt lgkmcnt(4)
	v_mfma_f32_32x32x16_bf16 v[0:15], v[248:251], v[84:87], v[0:15]
	ds_read_b128 v[248:251], v170 offset:22592
	s_waitcnt vmcnt(13) lgkmcnt(4)
	v_mfma_f32_32x32x16_bf16 v[64:79], v[166:169], v[88:91], v[64:79]
	ds_read_b128 v[166:169], v170 offset:4192
	s_waitcnt lgkmcnt(4)
	v_mfma_f32_32x32x16_bf16 v[48:63], v[172:175], v[88:91], v[48:63]
	ds_read_b128 v[172:175], v170 offset:8800
	s_waitcnt lgkmcnt(4)
	v_mfma_f32_32x32x16_bf16 v[32:47], v[242:245], v[88:91], v[32:47]
	ds_read_b128 v[242:245], v170 offset:13408
	s_waitcnt lgkmcnt(4)
	v_mfma_f32_32x32x16_bf16 v[16:31], v[186:189], v[88:91], v[16:31]
	ds_read_b128 v[186:189], v170 offset:22624
	s_waitcnt lgkmcnt(4)
	v_mfma_f32_32x32x16_bf16 v[0:15], v[248:251], v[88:91], v[0:15]
	ds_read_b128 v[248:251], v170 offset:18016
	s_waitcnt vmcnt(12) lgkmcnt(4)
	v_mfma_f32_32x32x16_bf16 v[64:79], v[166:169], v[92:95], v[64:79]
	s_waitcnt lgkmcnt(3)
	v_mfma_f32_32x32x16_bf16 v[48:63], v[172:175], v[92:95], v[48:63]
	s_waitcnt lgkmcnt(2)
	v_mfma_f32_32x32x16_bf16 v[32:47], v[242:245], v[92:95], v[32:47]
	s_waitcnt lgkmcnt(1)
	v_mfma_f32_32x32x16_bf16 v[0:15], v[186:189], v[92:95], v[0:15]
	s_waitcnt lgkmcnt(0)
	v_mfma_f32_32x32x16_bf16 v[16:31], v[248:251], v[92:95], v[16:31]
	s_cbranch_vccnz .LBB0_301
	s_and_b64 vcc, exec, s[42:43]
	s_cbranch_vccz .LBB0_298
	s_and_b64 s[22:23], s[76:77], exec
	s_cselect_b32 s24, 0, s97
	s_add_i32 s25, s90, 0x100
	s_and_b64 s[22:23], s[76:77], exec
	s_cselect_b32 s22, s25, s91
	v_add_u32_e32 v80, s22, v155
	v_mov_b32_e32 v81, s24
	s_cbranch_execz .LBB0_299
	s_branch .LBB0_300

; __device__ __forceinline__ int crow(int i, int h) { return (i & 3) + 8 * (i >> 2) + 4 * h; }
; __device__ __forceinline__ void attnA_unit(LAS unsigned char* lds, const Args& A, int unit) {
;     ...
;                 const bool edge = (i0 < 64) || (i0 + 96 > L);
;                 float mxp[2] = {-1e30f, -1e30f};
; #pragma unroll
;                 for (int kt = 0; kt < 5; ++kt)
; #pragma unroll
;                     for (int i = 0; i < 16; ++i) {
;                         const int cr = crow(i, 0);
;                         float v = S[kt][i] * QK_C + bl[32 * kt + cr + 4 * hh - ql + 32];
;                         if (edge) { const int kidx = i0 - 64 + 32 * kt + cr + 4 * hh; if (kidx < 0 || kidx >= L) v = -1e30f; }
;                         S[kt][i] = v; mxp[i & 1] = fmaxf(mxp[i & 1], v);
;                     }
;                 float mx = fmaxf(mxp[0], mxp[1]);
;                 mx = fmaxf(mx, __shfl_xor(mx, 32));
.LBB0_301:
	v_cmp_gt_i32_e32 vcc, 64, v162
	v_cmp_lt_i32_e64 s[22:23], s99, v162
	v_add_u32_e32 v165, v162, v179
	s_or_b64 vcc, vcc, s[22:23]
	s_cmp_eq_u64 vcc, 0
	s_cbranch_scc1 .LmixA_fast
	s_cmp_eq_u64 vcc, exec
	s_cbranch_scc1 .LmixA_medium
	v_cmp_lt_i32_e64 s[22:23], -1, v165
	v_cmp_gt_i32_e64 s[24:25], s87, v165
	s_waitcnt lgkmcnt(1)
	v_mul_f32_e32 v64, 0x3e38aa3b, v64
	s_and_b64 s[22:23], s[22:23], s[24:25]
	v_mul_f32_e32 v167, 0x3e38aa3b, v65
	v_add_u32_e32 v65, 1, v165
	v_cndmask_b32_e64 v166, v221, v64, s[22:23]
	v_cmp_lt_i32_e64 s[22:23], -1, v65
	v_cmp_gt_i32_e64 s[24:25], s87, v65
	v_cndmask_b32_e32 v64, v64, v166, vcc
	s_and_b64 s[22:23], s[22:23], s[24:25]
	v_add_u32_e32 v166, 2, v165
	v_cndmask_b32_e64 v65, v221, v167, s[22:23]
	v_cmp_lt_i32_e64 s[22:23], -1, v166
	v_cmp_gt_i32_e64 s[24:25], s87, v166
	s_waitcnt lgkmcnt(0)
	v_mul_f32_e32 v66, 0x3e38aa3b, v66
	s_and_b64 s[22:23], s[22:23], s[24:25]
	v_cndmask_b32_e64 v166, v221, v66, s[22:23]
	v_cndmask_b32_e32 v65, v167, v65, vcc
	v_cndmask_b32_e32 v66, v66, v166, vcc
	v_mul_f32_e32 v169, 0x3e38aa3b, v67
	v_add_u32_e32 v67, 3, v165
	v_cmp_lt_i32_e64 s[22:23], -1, v67
	v_cmp_gt_i32_e64 s[24:25], s87, v67
	s_and_b64 s[22:23], s[22:23], s[24:25]
	v_cndmask_b32_e64 v67, v221, v169, s[22:23]
	v_cndmask_b32_e32 v67, v169, v67, vcc
	s_mov_b32 s22, 0xf149f2ca
	s_waitcnt lgkmcnt(1)
	v_mul_f32_e32 v68, 0x3e38aa3b, v68
	v_add_u32_e32 v166, 8, v165
	v_max3_f32 v171, v65, s22, v67
	v_cmp_lt_i32_e64 s[22:23], -1, v166
	v_cmp_gt_i32_e64 s[24:25], s87, v166
	s_and_b64 s[22:23], s[22:23], s[24:25]
	v_mul_f32_e32 v167, 0x3e38aa3b, v69
	v_add_u32_e32 v69, 9, v165
	v_cndmask_b32_e64 v166, v221, v68, s[22:23]
	v_cmp_lt_i32_e64 s[22:23], -1, v69
	v_cmp_gt_i32_e64 s[24:25], s87, v69
	v_cndmask_b32_e32 v68, v68, v166, vcc
	s_and_b64 s[22:23], s[22:23], s[24:25]
	v_add_u32_e32 v166, 10, v165
	v_cndmask_b32_e64 v69, v221, v167, s[22:23]
	v_cmp_lt_i32_e64 s[22:23], -1, v166
	v_cmp_gt_i32_e64 s[24:25], s87, v166
	s_waitcnt lgkmcnt(0)
	v_mul_f32_e32 v70, 0x3e38aa3b, v70
	s_and_b64 s[22:23], s[22:23], s[24:25]
	v_cndmask_b32_e64 v166, v221, v70, s[22:23]
	v_cndmask_b32_e32 v69, v167, v69, vcc
	v_cndmask_b32_e32 v70, v70, v166, vcc
	v_mul_f32_e32 v169, 0x3e38aa3b, v71
	v_add_u32_e32 v71, 11, v165
	v_cmp_lt_i32_e64 s[22:23], -1, v71
	v_cmp_gt_i32_e64 s[24:25], s87, v71
	s_and_b64 s[22:23], s[22:23], s[24:25]
	v_cndmask_b32_e64 v71, v221, v169, s[22:23]
	v_cndmask_b32_e32 v71, v169, v71, vcc
	s_waitcnt lgkmcnt(1)
	v_mul_f32_e32 v72, 0x3e38aa3b, v72
	v_add_u32_e32 v166, 16, v165
	v_cmp_lt_i32_e64 s[22:23], -1, v166
	v_cmp_gt_i32_e64 s[24:25], s87, v166
	s_and_b64 s[22:23], s[22:23], s[24:25]
	v_mul_f32_e32 v167, 0x3e38aa3b, v73
	v_add_u32_e32 v73, 17, v165
	v_cndmask_b32_e64 v166, v221, v72, s[22:23]
	v_cmp_lt_i32_e64 s[22:23], -1, v73
	v_cmp_gt_i32_e64 s[24:25], s87, v73
	v_cndmask_b32_e32 v72, v72, v166, vcc
	s_and_b64 s[22:23], s[22:23], s[24:25]
	v_add_u32_e32 v166, 18, v165
	v_cndmask_b32_e64 v73, v221, v167, s[22:23]
	v_cmp_lt_i32_e64 s[22:23], -1, v166
	v_cmp_gt_i32_e64 s[24:25], s87, v166
	s_waitcnt lgkmcnt(0)
	v_mul_f32_e32 v74, 0x3e38aa3b, v74
	s_and_b64 s[22:23], s[22:23], s[24:25]
	v_cndmask_b32_e64 v166, v221, v74, s[22:23]
	v_cndmask_b32_e32 v73, v167, v73, vcc
	v_cndmask_b32_e32 v74, v74, v166, vcc
	v_mul_f32_e32 v169, 0x3e38aa3b, v75
	v_add_u32_e32 v75, 19, v165
	v_cmp_lt_i32_e64 s[22:23], -1, v75
	v_cmp_gt_i32_e64 s[24:25], s87, v75
	s_and_b64 s[22:23], s[22:23], s[24:25]
	v_cndmask_b32_e64 v75, v221, v169, s[22:23]
	v_cndmask_b32_e32 v168, v169, v75, vcc
	s_waitcnt lgkmcnt(0)
	v_mul_f32_e32 v75, 0x3e38aa3b, v76
	v_add_u32_e32 v76, 24, v165
	v_cmp_lt_i32_e64 s[22:23], -1, v76
	v_cmp_gt_i32_e64 s[24:25], s87, v76
	v_max_f32_e32 v170, 0xf149f2ca, v64
	s_and_b64 s[22:23], s[22:23], s[24:25]
	v_max3_f32 v170, v170, v66, v68
	v_cndmask_b32_e64 v76, v221, v75, s[22:23]
	v_max3_f32 v171, v171, v69, v71
	v_max3_f32 v170, v170, v70, v72
	v_cndmask_b32_e32 v75, v75, v76, vcc
	v_max3_f32 v169, v171, v73, v168
	v_max3_f32 v172, v170, v74, v75
	v_add_u32_e32 v76, 25, v165
	v_cmp_lt_i32_e64 s[22:23], -1, v76
	v_cmp_gt_i32_e64 s[24:25], s87, v76
	v_mul_f32_e32 v167, 0x3e38aa3b, v77
	s_and_b64 s[22:23], s[22:23], s[24:25]
	v_cndmask_b32_e64 v76, v221, v167, s[22:23]
	v_cndmask_b32_e32 v76, v167, v76, vcc
	s_waitcnt lgkmcnt(1)
	v_mul_f32_e32 v77, 0x3e38aa3b, v78
	v_add_u32_e32 v78, 26, v165
	v_cmp_lt_i32_e64 s[22:23], -1, v78
	v_cmp_gt_i32_e64 s[24:25], s87, v78
	s_and_b64 s[22:23], s[22:23], s[24:25]
	v_cndmask_b32_e64 v78, v221, v77, s[22:23]
	v_cndmask_b32_e32 v77, v77, v78, vcc
	v_add_u32_e32 v78, 27, v165
	v_cmp_lt_i32_e64 s[22:23], -1, v78
	v_cmp_gt_i32_e64 s[24:25], s87, v78
	v_mul_f32_e32 v171, 0x3e38aa3b, v79
	s_and_b64 s[22:23], s[22:23], s[24:25]
	v_cndmask_b32_e64 v78, v221, v171, s[22:23]
	s_waitcnt lgkmcnt(0)
	v_mul_f32_e32 v48, 0x3e38aa3b, v48
	v_add_u32_e32 v166, 32, v165
	v_cndmask_b32_e32 v78, v171, v78, vcc
	v_cmp_lt_i32_e64 s[22:23], -1, v166
	v_cmp_gt_i32_e64 s[24:25], s87, v166
	s_and_b64 s[22:23], s[22:23], s[24:25]
	v_mul_f32_e32 v167, 0x3e38aa3b, v49
	v_add_u32_e32 v49, 33, v165
	v_cndmask_b32_e64 v166, v221, v48, s[22:23]
	v_cmp_lt_i32_e64 s[22:23], -1, v49
	v_cmp_gt_i32_e64 s[24:25], s87, v49
	v_cndmask_b32_e32 v48, v48, v166, vcc
	s_and_b64 s[22:23], s[22:23], s[24:25]
	v_add_u32_e32 v166, 34, v165
	v_cndmask_b32_e64 v49, v221, v167, s[22:23]
	v_cmp_lt_i32_e64 s[22:23], -1, v166
	v_cmp_gt_i32_e64 s[24:25], s87, v166
	s_waitcnt lgkmcnt(0)
; __device__ __forceinline__ int crow(int i, int h) { return (i & 3) + 8 * (i >> 2) + 4 * h; }
; __device__ __forceinline__ void attnA_unit(LAS unsigned char* lds, const Args& A, int unit) {
;     ...
;                 const bool edge = (i0 < 64) || (i0 + 96 > L);
;                 float mxp[2] = {-1e30f, -1e30f};
; #pragma unroll
;                 for (int kt = 0; kt < 5; ++kt)
; #pragma unroll
;                     for (int i = 0; i < 16; ++i) {
;                         const int cr = crow(i, 0);
;                         float v = S[kt][i] * QK_C + bl[32 * kt + cr + 4 * hh - ql + 32];
;                         if (edge) { const int kidx = i0 - 64 + 32 * kt + cr + 4 * hh; if (kidx < 0 || kidx >= L) v = -1e30f; }
;                         S[kt][i] = v; mxp[i & 1] = fmaxf(mxp[i & 1], v);
;                     }
;                 float mx = fmaxf(mxp[0], mxp[1]);
;                 mx = fmaxf(mx, __shfl_xor(mx, 32));
	v_mul_f32_e32 v50, 0x3e38aa3b, v50
	s_and_b64 s[22:23], s[22:23], s[24:25]
	v_cndmask_b32_e64 v166, v221, v50, s[22:23]
	v_cndmask_b32_e32 v49, v167, v49, vcc
	v_cndmask_b32_e32 v50, v50, v166, vcc
	v_mul_f32_e32 v171, 0x3e38aa3b, v51
	v_add_u32_e32 v51, 35, v165
	v_cmp_lt_i32_e64 s[22:23], -1, v51
	v_cmp_gt_i32_e64 s[24:25], s87, v51
	s_and_b64 s[22:23], s[22:23], s[24:25]
	v_cndmask_b32_e64 v51, v221, v171, s[22:23]
	v_cndmask_b32_e32 v51, v171, v51, vcc
	s_waitcnt lgkmcnt(1)
	v_mul_f32_e32 v52, 0x3e38aa3b, v52
	v_add_u32_e32 v166, 40, v165
	v_cmp_lt_i32_e64 s[22:23], -1, v166
	v_cmp_gt_i32_e64 s[24:25], s87, v166
	s_and_b64 s[22:23], s[22:23], s[24:25]
	v_mul_f32_e32 v167, 0x3e38aa3b, v53
	v_add_u32_e32 v53, 41, v165
	v_cndmask_b32_e64 v166, v221, v52, s[22:23]
	v_cmp_lt_i32_e64 s[22:23], -1, v53
	v_cmp_gt_i32_e64 s[24:25], s87, v53
	v_cndmask_b32_e32 v52, v52, v166, vcc
	s_and_b64 s[22:23], s[22:23], s[24:25]
	v_add_u32_e32 v166, 42, v165
	v_cndmask_b32_e64 v53, v221, v167, s[22:23]
	v_cmp_lt_i32_e64 s[22:23], -1, v166
	v_cmp_gt_i32_e64 s[24:25], s87, v166
	s_waitcnt lgkmcnt(0)
	v_mul_f32_e32 v54, 0x3e38aa3b, v54
	s_and_b64 s[22:23], s[22:23], s[24:25]
	v_cndmask_b32_e64 v166, v221, v54, s[22:23]
	v_cndmask_b32_e32 v53, v167, v53, vcc
	v_cndmask_b32_e32 v54, v54, v166, vcc
	v_mul_f32_e32 v171, 0x3e38aa3b, v55
	v_add_u32_e32 v55, 43, v165
	v_cmp_lt_i32_e64 s[22:23], -1, v55
	v_cmp_gt_i32_e64 s[24:25], s87, v55
	s_and_b64 s[22:23], s[22:23], s[24:25]
	v_cndmask_b32_e64 v55, v221, v171, s[22:23]
	v_cndmask_b32_e32 v55, v171, v55, vcc
	s_waitcnt lgkmcnt(1)
	v_mul_f32_e32 v56, 0x3e38aa3b, v56
	v_add_u32_e32 v166, 48, v165
	v_cmp_lt_i32_e64 s[22:23], -1, v166
	v_cmp_gt_i32_e64 s[24:25], s87, v166
	s_and_b64 s[22:23], s[22:23], s[24:25]
	v_mul_f32_e32 v167, 0x3e38aa3b, v57
	v_add_u32_e32 v57, 49, v165
	v_cndmask_b32_e64 v166, v221, v56, s[22:23]
	v_cmp_lt_i32_e64 s[22:23], -1, v57
	v_cmp_gt_i32_e64 s[24:25], s87, v57
	v_cndmask_b32_e32 v56, v56, v166, vcc
	s_and_b64 s[22:23], s[22:23], s[24:25]
	v_add_u32_e32 v166, 50, v165
	v_cndmask_b32_e64 v57, v221, v167, s[22:23]
	v_cmp_lt_i32_e64 s[22:23], -1, v166
	v_cmp_gt_i32_e64 s[24:25], s87, v166
	s_waitcnt lgkmcnt(0)
	v_mul_f32_e32 v58, 0x3e38aa3b, v58
	s_and_b64 s[22:23], s[22:23], s[24:25]
	v_cndmask_b32_e64 v166, v221, v58, s[22:23]
	v_cndmask_b32_e32 v57, v167, v57, vcc
	v_cndmask_b32_e32 v58, v58, v166, vcc
	v_mul_f32_e32 v171, 0x3e38aa3b, v59
	v_add_u32_e32 v59, 51, v165
	v_cmp_lt_i32_e64 s[22:23], -1, v59
	v_cmp_gt_i32_e64 s[24:25], s87, v59
	s_and_b64 s[22:23], s[22:23], s[24:25]
	v_cndmask_b32_e64 v59, v221, v171, s[22:23]
	v_cndmask_b32_e32 v59, v171, v59, vcc
	s_waitcnt lgkmcnt(1)
	v_mul_f32_e32 v60, 0x3e38aa3b, v60
	v_add_u32_e32 v166, 56, v165
	v_cmp_lt_i32_e64 s[22:23], -1, v166
	v_cmp_gt_i32_e64 s[24:25], s87, v166
	s_and_b64 s[22:23], s[22:23], s[24:25]
	v_mul_f32_e32 v167, 0x3e38aa3b, v61
	v_add_u32_e32 v61, 57, v165
	v_cndmask_b32_e64 v166, v221, v60, s[22:23]
	v_cmp_lt_i32_e64 s[22:23], -1, v61
	v_cmp_gt_i32_e64 s[24:25], s87, v61
	s_and_b64 s[22:23], s[22:23], s[24:25]
	v_cndmask_b32_e64 v61, v221, v167, s[22:23]
	v_cndmask_b32_e32 v61, v167, v61, vcc
	v_add_u32_e32 v167, 58, v165
	v_max3_f32 v79, v169, v76, v78
	v_max3_f32 v169, v172, v77, v48
	v_cmp_lt_i32_e64 s[22:23], -1, v167
	v_cmp_gt_i32_e64 s[24:25], s87, v167
	v_max3_f32 v169, v169, v50, v52
	s_waitcnt lgkmcnt(0)
	v_mul_f32_e32 v62, 0x3e38aa3b, v62
	s_and_b64 s[22:23], s[22:23], s[24:25]
	v_max3_f32 v169, v169, v54, v56
	v_cndmask_b32_e32 v60, v60, v166, vcc
	v_cndmask_b32_e64 v167, v221, v62, s[22:23]
	v_max3_f32 v166, v169, v58, v60
	v_cndmask_b32_e32 v169, v62, v167, vcc
	v_add_u32_e32 v62, 59, v165
	v_mul_f32_e32 v171, 0x3e38aa3b, v63
	v_cmp_lt_i32_e64 s[22:23], -1, v62
	v_cmp_gt_i32_e64 s[24:25], s87, v62
	s_and_b64 s[22:23], s[22:23], s[24:25]
	v_cndmask_b32_e64 v167, v221, v171, s[22:23]
	v_cndmask_b32_e32 v208, v171, v167, vcc
	v_max3_f32 v79, v79, v49, v51
	s_waitcnt lgkmcnt(0)
	v_mul_f32_e32 v32, 0x3e38aa3b, v32
	v_add_u32_e32 v62, 64, v165
	v_cmp_lt_i32_e64 s[22:23], -1, v62
	v_cmp_gt_i32_e64 s[24:25], s87, v62
	s_and_b64 s[22:23], s[22:23], s[24:25]
	v_cndmask_b32_e64 v62, v221, v32, s[22:23]
	v_cndmask_b32_e32 v209, v32, v62, vcc
	v_max3_f32 v32, v166, v169, v209
	v_mul_f32_e32 v63, 0x3e38aa3b, v33
	v_add_u32_e32 v33, 0x41, v165
	v_cmp_lt_i32_e64 s[22:23], -1, v33
	v_cmp_gt_i32_e64 s[24:25], s87, v33
	s_and_b64 s[22:23], s[22:23], s[24:25]
	v_cndmask_b32_e64 v33, v221, v63, s[22:23]
	v_cndmask_b32_e32 v210, v63, v33, vcc
	s_waitcnt lgkmcnt(1)
	v_mul_f32_e32 v33, 0x3e38aa3b, v34
	v_add_u32_e32 v34, 0x42, v165
	v_cmp_lt_i32_e64 s[22:23], -1, v34
	v_cmp_gt_i32_e64 s[24:25], s87, v34
	s_and_b64 s[22:23], s[22:23], s[24:25]
	v_cndmask_b32_e64 v34, v221, v33, s[22:23]
	v_cndmask_b32_e32 v33, v33, v34, vcc
	v_add_u32_e32 v34, 0x43, v165
	v_cmp_lt_i32_e64 s[22:23], -1, v34
	v_cmp_gt_i32_e64 s[24:25], s87, v34
	v_mul_f32_e32 v167, 0x3e38aa3b, v35
	s_and_b64 s[22:23], s[22:23], s[24:25]
	s_waitcnt lgkmcnt(0)
	v_mul_f32_e32 v35, 0x3e38aa3b, v36
	v_add_u32_e32 v36, 0x48, v165
	v_cndmask_b32_e64 v34, v221, v167, s[22:23]
	v_cmp_lt_i32_e64 s[22:23], -1, v36
	v_cmp_gt_i32_e64 s[24:25], s87, v36
	s_and_b64 s[22:23], s[22:23], s[24:25]
	v_cndmask_b32_e32 v34, v167, v34, vcc
	v_cndmask_b32_e64 v36, v221, v35, s[22:23]
	v_cndmask_b32_e32 v35, v35, v36, vcc
	v_add_u32_e32 v36, 0x49, v165
	v_cmp_lt_i32_e64 s[22:23], -1, v36
	v_cmp_gt_i32_e64 s[24:25], s87, v36
	v_mul_f32_e32 v63, 0x3e38aa3b, v37
	s_and_b64 s[22:23], s[22:23], s[24:25]
	v_cndmask_b32_e64 v36, v221, v63, s[22:23]
	v_cndmask_b32_e32 v36, v63, v36, vcc
	s_waitcnt lgkmcnt(1)
; __device__ __forceinline__ int crow(int i, int h) { return (i & 3) + 8 * (i >> 2) + 4 * h; }
; __device__ __forceinline__ void attnA_unit(LAS unsigned char* lds, const Args& A, int unit) {
;     ...
;                 const bool edge = (i0 < 64) || (i0 + 96 > L);
;                 float mxp[2] = {-1e30f, -1e30f};
; #pragma unroll
;                 for (int kt = 0; kt < 5; ++kt)
; #pragma unroll
;                     for (int i = 0; i < 16; ++i) {
;                         const int cr = crow(i, 0);
;                         float v = S[kt][i] * QK_C + bl[32 * kt + cr + 4 * hh - ql + 32];
;                         if (edge) { const int kidx = i0 - 64 + 32 * kt + cr + 4 * hh; if (kidx < 0 || kidx >= L) v = -1e30f; }
;                         S[kt][i] = v; mxp[i & 1] = fmaxf(mxp[i & 1], v);
;                     }
;                 float mx = fmaxf(mxp[0], mxp[1]);
;                 mx = fmaxf(mx, __shfl_xor(mx, 32));
	v_mul_f32_e32 v37, 0x3e38aa3b, v38
	v_add_u32_e32 v38, 0x4a, v165
	v_cmp_lt_i32_e64 s[22:23], -1, v38
	v_cmp_gt_i32_e64 s[24:25], s87, v38
	s_and_b64 s[22:23], s[22:23], s[24:25]
	v_cndmask_b32_e64 v38, v221, v37, s[22:23]
	v_cndmask_b32_e32 v37, v37, v38, vcc
	v_add_u32_e32 v38, 0x4b, v165
	v_cmp_lt_i32_e64 s[22:23], -1, v38
	v_cmp_gt_i32_e64 s[24:25], s87, v38
	v_mul_f32_e32 v167, 0x3e38aa3b, v39
	s_and_b64 s[22:23], s[22:23], s[24:25]
	s_waitcnt lgkmcnt(0)
	v_mul_f32_e32 v39, 0x3e38aa3b, v40
	v_add_u32_e32 v40, 0x50, v165
	v_cndmask_b32_e64 v38, v221, v167, s[22:23]
	v_cmp_lt_i32_e64 s[22:23], -1, v40
	v_cmp_gt_i32_e64 s[24:25], s87, v40
	s_and_b64 s[22:23], s[22:23], s[24:25]
	v_cndmask_b32_e32 v38, v167, v38, vcc
	v_cndmask_b32_e64 v40, v221, v39, s[22:23]
	v_cndmask_b32_e32 v39, v39, v40, vcc
	v_add_u32_e32 v40, 0x51, v165
	v_cmp_lt_i32_e64 s[22:23], -1, v40
	v_cmp_gt_i32_e64 s[24:25], s87, v40
	v_mul_f32_e32 v63, 0x3e38aa3b, v41
	s_and_b64 s[22:23], s[22:23], s[24:25]
	v_cndmask_b32_e64 v40, v221, v63, s[22:23]
	v_cndmask_b32_e32 v40, v63, v40, vcc
	s_waitcnt lgkmcnt(1)
	v_mul_f32_e32 v41, 0x3e38aa3b, v42
	v_add_u32_e32 v42, 0x52, v165
	v_cmp_lt_i32_e64 s[22:23], -1, v42
	v_cmp_gt_i32_e64 s[24:25], s87, v42
	s_and_b64 s[22:23], s[22:23], s[24:25]
	v_cndmask_b32_e64 v42, v221, v41, s[22:23]
	v_cndmask_b32_e32 v41, v41, v42, vcc
	v_add_u32_e32 v42, 0x53, v165
	v_cmp_lt_i32_e64 s[22:23], -1, v42
	v_cmp_gt_i32_e64 s[24:25], s87, v42
	v_mul_f32_e32 v167, 0x3e38aa3b, v43
	s_and_b64 s[22:23], s[22:23], s[24:25]
	s_waitcnt lgkmcnt(0)
	v_mul_f32_e32 v43, 0x3e38aa3b, v44
	v_add_u32_e32 v44, 0x58, v165
	v_cndmask_b32_e64 v42, v221, v167, s[22:23]
	v_cmp_lt_i32_e64 s[22:23], -1, v44
	v_cmp_gt_i32_e64 s[24:25], s87, v44
	s_and_b64 s[22:23], s[22:23], s[24:25]
	v_cndmask_b32_e32 v42, v167, v42, vcc
	v_cndmask_b32_e64 v44, v221, v43, s[22:23]
	v_cndmask_b32_e32 v43, v43, v44, vcc
	v_add_u32_e32 v44, 0x59, v165
	v_cmp_lt_i32_e64 s[22:23], -1, v44
	v_cmp_gt_i32_e64 s[24:25], s87, v44
	v_mul_f32_e32 v63, 0x3e38aa3b, v45
	s_and_b64 s[22:23], s[22:23], s[24:25]
	v_cndmask_b32_e64 v44, v221, v63, s[22:23]
	v_cndmask_b32_e32 v44, v63, v44, vcc
	s_waitcnt lgkmcnt(1)
	v_mul_f32_e32 v45, 0x3e38aa3b, v46
	v_add_u32_e32 v46, 0x5a, v165
	v_cmp_lt_i32_e64 s[22:23], -1, v46
	v_cmp_gt_i32_e64 s[24:25], s87, v46
	s_and_b64 s[22:23], s[22:23], s[24:25]
	v_cndmask_b32_e64 v46, v221, v45, s[22:23]
	v_cndmask_b32_e32 v45, v45, v46, vcc
	v_add_u32_e32 v46, 0x5b, v165
	v_cmp_lt_i32_e64 s[22:23], -1, v46
	v_cmp_gt_i32_e64 s[24:25], s87, v46
	v_mul_f32_e32 v167, 0x3e38aa3b, v47
	s_and_b64 s[22:23], s[22:23], s[24:25]
	v_cndmask_b32_e64 v46, v221, v167, s[22:23]
	s_waitcnt lgkmcnt(0)
	v_mul_f32_e32 v16, 0x3e38aa3b, v16
	v_add_u32_e32 v62, 0x60, v165
	v_cndmask_b32_e32 v46, v167, v46, vcc
	v_cmp_lt_i32_e64 s[22:23], -1, v62
	v_cmp_gt_i32_e64 s[24:25], s87, v62
	s_and_b64 s[22:23], s[22:23], s[24:25]
	v_mul_f32_e32 v63, 0x3e38aa3b, v17
	v_add_u32_e32 v17, 0x61, v165
	v_cndmask_b32_e64 v62, v221, v16, s[22:23]
	v_cmp_lt_i32_e64 s[22:23], -1, v17
	v_cmp_gt_i32_e64 s[24:25], s87, v17
	v_max3_f32 v79, v79, v53, v55
	v_cndmask_b32_e32 v16, v16, v62, vcc
	s_and_b64 s[22:23], s[22:23], s[24:25]
	v_add_u32_e32 v62, 0x62, v165
	v_max3_f32 v79, v79, v57, v59
	v_cndmask_b32_e64 v17, v221, v63, s[22:23]
	v_cmp_lt_i32_e64 s[22:23], -1, v62
	v_cmp_gt_i32_e64 s[24:25], s87, v62
	v_max3_f32 v79, v79, v61, v208
	s_waitcnt lgkmcnt(0)
	v_mul_f32_e32 v18, 0x3e38aa3b, v18
	s_and_b64 s[22:23], s[22:23], s[24:25]
	v_mul_f32_e32 v167, 0x3e38aa3b, v19
	v_add_u32_e32 v19, 0x63, v165
	v_max3_f32 v79, v79, v210, v34
	v_cndmask_b32_e64 v62, v221, v18, s[22:23]
	v_cmp_lt_i32_e64 s[22:23], -1, v19
	v_cmp_gt_i32_e64 s[24:25], s87, v19
	v_max3_f32 v79, v79, v36, v38
	v_cndmask_b32_e32 v17, v63, v17, vcc
	v_cndmask_b32_e32 v18, v18, v62, vcc
	s_and_b64 s[22:23], s[22:23], s[24:25]
	v_max3_f32 v79, v79, v40, v42
	v_cndmask_b32_e64 v19, v221, v167, s[22:23]
	v_max3_f32 v47, v79, v44, v46
	v_cndmask_b32_e32 v19, v167, v19, vcc
	v_max3_f32 v79, v47, v17, v19
	v_add_u32_e32 v47, 0x68, v165
	v_cmp_lt_i32_e64 s[22:23], -1, v47
	v_cmp_gt_i32_e64 s[24:25], s87, v47
	s_waitcnt lgkmcnt(1)
	v_mul_f32_e32 v20, 0x3e38aa3b, v20
	s_and_b64 s[22:23], s[22:23], s[24:25]
	v_mul_f32_e32 v63, 0x3e38aa3b, v21
	v_add_u32_e32 v21, 0x69, v165
	v_cndmask_b32_e64 v47, v221, v20, s[22:23]
	v_cmp_lt_i32_e64 s[22:23], -1, v21
	v_cmp_gt_i32_e64 s[24:25], s87, v21
	s_and_b64 s[22:23], s[22:23], s[24:25]
	v_cndmask_b32_e64 v21, v221, v63, s[22:23]
	v_cndmask_b32_e32 v20, v20, v47, vcc
	v_cndmask_b32_e32 v47, v63, v21, vcc
	s_waitcnt lgkmcnt(0)
	v_mul_f32_e32 v21, 0x3e38aa3b, v22
	v_add_u32_e32 v22, 0x6a, v165
	v_cmp_lt_i32_e64 s[22:23], -1, v22
	v_cmp_gt_i32_e64 s[24:25], s87, v22
	s_and_b64 s[22:23], s[22:23], s[24:25]
	v_cndmask_b32_e64 v22, v221, v21, s[22:23]
	v_cndmask_b32_e32 v211, v21, v22, vcc
	v_add_u32_e32 v21, 0x6b, v165
	v_cmp_lt_i32_e64 s[22:23], -1, v21
	v_cmp_gt_i32_e64 s[24:25], s87, v21
	v_mul_f32_e32 v167, 0x3e38aa3b, v23
	s_and_b64 s[22:23], s[22:23], s[24:25]
	v_cndmask_b32_e64 v21, v221, v167, s[22:23]
	v_cndmask_b32_e32 v23, v167, v21, vcc
	s_waitcnt lgkmcnt(1)
	v_mul_f32_e32 v22, 0x3e38aa3b, v24
	v_add_u32_e32 v24, 0x70, v165
	v_cmp_lt_i32_e64 s[22:23], -1, v24
	v_cmp_gt_i32_e64 s[24:25], s87, v24
	s_and_b64 s[22:23], s[22:23], s[24:25]
	v_cndmask_b32_e64 v24, v221, v22, s[22:23]
	v_cndmask_b32_e32 v22, v22, v24, vcc
	v_add_u32_e32 v24, 0x71, v165
	v_cmp_lt_i32_e64 s[22:23], -1, v24
	v_cmp_gt_i32_e64 s[24:25], s87, v24
	v_mul_f32_e32 v63, 0x3e38aa3b, v25
	s_and_b64 s[22:23], s[22:23], s[24:25]
	s_waitcnt lgkmcnt(0)
; __device__ __forceinline__ int crow(int i, int h) { return (i & 3) + 8 * (i >> 2) + 4 * h; }
; __device__ __forceinline__ void attnA_unit(LAS unsigned char* lds, const Args& A, int unit) {
;     ...
;                 const bool edge = (i0 < 64) || (i0 + 96 > L);
;                 float mxp[2] = {-1e30f, -1e30f};
; #pragma unroll
;                 for (int kt = 0; kt < 5; ++kt)
; #pragma unroll
;                     for (int i = 0; i < 16; ++i) {
;                         const int cr = crow(i, 0);
;                         float v = S[kt][i] * QK_C + bl[32 * kt + cr + 4 * hh - ql + 32];
;                         if (edge) { const int kidx = i0 - 64 + 32 * kt + cr + 4 * hh; if (kidx < 0 || kidx >= L) v = -1e30f; }
;                         S[kt][i] = v; mxp[i & 1] = fmaxf(mxp[i & 1], v);
;                     }
;                 float mx = fmaxf(mxp[0], mxp[1]);
;                 mx = fmaxf(mx, __shfl_xor(mx, 32));
	v_mul_f32_e32 v25, 0x3e38aa3b, v26
	v_add_u32_e32 v26, 0x72, v165
	v_cndmask_b32_e64 v24, v221, v63, s[22:23]
	v_cmp_lt_i32_e64 s[22:23], -1, v26
	v_cmp_gt_i32_e64 s[24:25], s87, v26
	s_and_b64 s[22:23], s[22:23], s[24:25]
	v_cndmask_b32_e64 v26, v221, v25, s[22:23]
	v_cndmask_b32_e32 v24, v63, v24, vcc
	v_cndmask_b32_e32 v25, v25, v26, vcc
	v_add_u32_e32 v26, 0x73, v165
	v_cmp_lt_i32_e64 s[22:23], -1, v26
	v_cmp_gt_i32_e64 s[24:25], s87, v26
	v_mul_f32_e32 v167, 0x3e38aa3b, v27
	s_and_b64 s[22:23], s[22:23], s[24:25]
	v_cndmask_b32_e64 v26, v221, v167, s[22:23]
	v_max3_f32 v21, v79, v47, v23
	v_cndmask_b32_e32 v27, v167, v26, vcc
	v_add_u32_e32 v26, 0x78, v165
	v_max3_f32 v79, v21, v24, v27
	s_waitcnt lgkmcnt(0)
	v_mul_f32_e32 v21, 0x3e38aa3b, v28
	v_cmp_lt_i32_e64 s[22:23], -1, v26
	v_cmp_gt_i32_e64 s[24:25], s87, v26
	v_mul_f32_e32 v63, 0x3e38aa3b, v29
	s_and_b64 s[22:23], s[22:23], s[24:25]
	v_cndmask_b32_e64 v26, v221, v21, s[22:23]
	v_cndmask_b32_e32 v21, v21, v26, vcc
	v_add_u32_e32 v26, 0x79, v165
	v_cmp_lt_i32_e64 s[22:23], -1, v26
	v_cmp_gt_i32_e64 s[24:25], s87, v26
	s_and_b64 s[22:23], s[22:23], s[24:25]
	s_waitcnt lgkmcnt(0)
	v_mul_f32_e32 v28, 0x3e38aa3b, v30
	v_add_u32_e32 v30, 0x7a, v165
	v_cndmask_b32_e64 v26, v221, v63, s[22:23]
	v_cmp_lt_i32_e64 s[22:23], -1, v30
	v_cmp_gt_i32_e64 s[24:25], s87, v30
	s_and_b64 s[22:23], s[22:23], s[24:25]
	v_cndmask_b32_e64 v30, v221, v28, s[22:23]
	v_cndmask_b32_e32 v28, v28, v30, vcc
	v_add_u32_e32 v30, 0x7b, v165
	v_mul_f32_e32 v29, 0x3e38aa3b, v31
	v_cmp_lt_i32_e64 s[22:23], -1, v30
	v_cmp_gt_i32_e64 s[24:25], s87, v30
	v_max3_f32 v32, v32, v33, v35
	s_and_b64 s[22:23], s[22:23], s[24:25]
	v_max3_f32 v32, v32, v37, v39
	v_cndmask_b32_e64 v62, v221, v29, s[22:23]
	s_waitcnt lgkmcnt(0)
	v_mul_f32_e32 v0, 0x3e38aa3b, v0
	v_add_u32_e32 v30, 0x80, v165
	v_cmp_lt_i32_e64 s[22:23], -1, v30
	v_cmp_gt_i32_e64 s[24:25], s87, v30
	v_max3_f32 v32, v32, v41, v43
	s_and_b64 s[22:23], s[22:23], s[24:25]
	v_max3_f32 v32, v32, v45, v16
	v_cndmask_b32_e64 v30, v221, v0, s[22:23]
	v_max3_f32 v32, v32, v18, v20
	v_cndmask_b32_e32 v223, v0, v30, vcc
	v_mul_f32_e32 v31, 0x3e38aa3b, v1
	v_max3_f32 v32, v32, v211, v22
	v_max3_f32 v32, v32, v25, v21
	v_max3_f32 v30, v32, v28, v223
	v_add_u32_e32 v32, 0x81, v165
	v_cmp_lt_i32_e64 s[22:23], -1, v32
	v_cmp_gt_i32_e64 s[24:25], s87, v32
	s_and_b64 s[22:23], s[22:23], s[24:25]
	s_waitcnt lgkmcnt(0)
	v_mul_f32_e32 v0, 0x3e38aa3b, v2
	v_add_u32_e32 v2, 0x82, v165
	v_cndmask_b32_e64 v32, v221, v31, s[22:23]
	v_cmp_lt_i32_e64 s[22:23], -1, v2
	v_cmp_gt_i32_e64 s[24:25], s87, v2
	s_and_b64 s[22:23], s[22:23], s[24:25]
	v_cndmask_b32_e64 v2, v221, v0, s[22:23]
	v_cndmask_b32_e32 v225, v0, v2, vcc
	v_add_u32_e32 v0, 0x83, v165
	v_mul_f32_e32 v1, 0x3e38aa3b, v3
	v_cmp_lt_i32_e64 s[22:23], -1, v0
	v_cmp_gt_i32_e64 s[24:25], s87, v0
	s_and_b64 s[22:23], s[22:23], s[24:25]
	v_cndmask_b32_e64 v0, v221, v1, s[22:23]
	v_cndmask_b32_e32 v227, v1, v0, vcc
	v_add_u32_e32 v1, 0x88, v165
	v_cmp_lt_i32_e64 s[22:23], -1, v1
	v_cmp_gt_i32_e64 s[24:25], s87, v1
	s_waitcnt lgkmcnt(0)
	v_mul_f32_e32 v0, 0x3e38aa3b, v4
	s_and_b64 s[22:23], s[22:23], s[24:25]
	v_cndmask_b32_e64 v1, v221, v0, s[22:23]
	v_add_u32_e32 v2, 0x89, v165
	v_cndmask_b32_e32 v228, v0, v1, vcc
	v_cmp_lt_i32_e64 s[22:23], -1, v2
	v_cmp_gt_i32_e64 s[24:25], s87, v2
	v_mul_f32_e32 v3, 0x3e38aa3b, v5
	s_and_b64 s[22:23], s[22:23], s[24:25]
	v_cndmask_b32_e64 v2, v221, v3, s[22:23]
	v_cndmask_b32_e32 v230, v3, v2, vcc
	v_add_u32_e32 v2, 0x8a, v165
	v_cmp_lt_i32_e64 s[22:23], -1, v2
	v_cmp_gt_i32_e64 s[24:25], s87, v2
	s_waitcnt lgkmcnt(0)
	v_mul_f32_e32 v0, 0x3e38aa3b, v6
	s_and_b64 s[22:23], s[22:23], s[24:25]
	v_cndmask_b32_e64 v2, v221, v0, s[22:23]
	v_cndmask_b32_e32 v232, v0, v2, vcc
	v_add_u32_e32 v0, 0x8b, v165
	v_cmp_lt_i32_e64 s[22:23], -1, v0
	v_cmp_gt_i32_e64 s[24:25], s87, v0
	v_mul_f32_e32 v1, 0x3e38aa3b, v7
	s_and_b64 s[22:23], s[22:23], s[24:25]
	v_cndmask_b32_e64 v0, v221, v1, s[22:23]
	v_cndmask_b32_e32 v233, v1, v0, vcc
	v_add_u32_e32 v1, 0x90, v165
	v_cmp_lt_i32_e64 s[22:23], -1, v1
	v_cmp_gt_i32_e64 s[24:25], s87, v1
	s_waitcnt lgkmcnt(0)
	v_mul_f32_e32 v0, 0x3e38aa3b, v8
	s_and_b64 s[22:23], s[22:23], s[24:25]
	v_cndmask_b32_e64 v1, v221, v0, s[22:23]
	v_add_u32_e32 v2, 0x91, v165
	v_cndmask_b32_e32 v231, v0, v1, vcc
	v_cmp_lt_i32_e64 s[22:23], -1, v2
	v_cmp_gt_i32_e64 s[24:25], s87, v2
	v_mul_f32_e32 v3, 0x3e38aa3b, v9
	s_and_b64 s[22:23], s[22:23], s[24:25]
	v_cndmask_b32_e64 v2, v221, v3, s[22:23]
	v_cndmask_b32_e32 v234, v3, v2, vcc
	v_add_u32_e32 v2, 0x92, v165
	v_cmp_lt_i32_e64 s[22:23], -1, v2
	v_cmp_gt_i32_e64 s[24:25], s87, v2
	s_waitcnt lgkmcnt(0)
	v_mul_f32_e32 v0, 0x3e38aa3b, v10
	s_and_b64 s[22:23], s[22:23], s[24:25]
	v_cndmask_b32_e64 v2, v221, v0, s[22:23]
	v_cndmask_b32_e32 v235, v0, v2, vcc
	v_add_u32_e32 v0, 0x93, v165
	v_cmp_lt_i32_e64 s[22:23], -1, v0
	v_cmp_gt_i32_e64 s[24:25], s87, v0
	v_mul_f32_e32 v1, 0x3e38aa3b, v11
	s_and_b64 s[22:23], s[22:23], s[24:25]
	v_cndmask_b32_e64 v0, v221, v1, s[22:23]
	v_cndmask_b32_e32 v236, v1, v0, vcc
	v_add_u32_e32 v1, 0x98, v165
	v_cmp_lt_i32_e64 s[22:23], -1, v1
	v_cmp_gt_i32_e64 s[24:25], s87, v1
	s_waitcnt lgkmcnt(0)
	v_mul_f32_e32 v0, 0x3e38aa3b, v12
	s_and_b64 s[22:23], s[22:23], s[24:25]
	v_max3_f32 v4, v30, v225, v228
	v_cndmask_b32_e64 v1, v221, v0, s[22:23]
	v_max3_f32 v4, v4, v232, v231
	v_cndmask_b32_e32 v237, v0, v1, vcc
	v_max3_f32 v2, v4, v235, v237
	v_add_u32_e32 v4, 0x99, v165
	v_cmp_lt_i32_e64 s[22:23], -1, v4
	v_cmp_gt_i32_e64 s[24:25], s87, v4
	v_mul_f32_e32 v3, 0x3e38aa3b, v13
	s_and_b64 s[22:23], s[22:23], s[24:25]
	v_cndmask_b32_e64 v4, v221, v3, s[22:23]
	v_cndmask_b32_e32 v240, v3, v4, vcc
	v_add_u32_e32 v3, 0x9a, v165
	v_cmp_lt_i32_e64 s[22:23], -1, v3
	v_cmp_gt_i32_e64 s[24:25], s87, v3
	s_waitcnt lgkmcnt(0)
	v_mul_f32_e32 v0, 0x3e38aa3b, v14
	s_and_b64 s[22:23], s[22:23], s[24:25]
	v_cndmask_b32_e64 v3, v221, v0, s[22:23]
	v_cndmask_b32_e32 v26, v63, v26, vcc
	v_cndmask_b32_e32 v224, v29, v62, vcc
	v_cndmask_b32_e32 v239, v0, v3, vcc
	v_add_u32_e32 v0, 0x9b, v165
	v_max3_f32 v29, v79, v26, v224
	v_cndmask_b32_e32 v226, v31, v32, vcc
	v_cmp_lt_i32_e64 s[22:23], -1, v0
	v_cmp_gt_i32_e64 s[24:25], s87, v0
	v_max3_f32 v29, v29, v226, v227
	v_mul_f32_e32 v1, 0x3e38aa3b, v15
	s_and_b64 s[22:23], s[22:23], s[24:25]
	v_max3_f32 v5, v29, v230, v233
	v_cndmask_b32_e64 v0, v221, v1, s[22:23]
	v_max3_f32 v5, v5, v234, v236
	v_cndmask_b32_e32 v241, v1, v0, vcc
	v_max3_f32 v0, v5, v240, v241
	v_max3_f32 v0, v2, v239, v0
	s_branch .LmixA_join

; __device__ __forceinline__ int crow(int i, int h) { return (i & 3) + 8 * (i >> 2) + 4 * h; }
; __device__ __forceinline__ void attnA_unit(LAS unsigned char* lds, const Args& A, int unit) {
;     ...
;                 for (int kt = 0; kt < 5; ++kt)
; #pragma unroll
;                     for (int i = 0; i < 16; ++i) {
;                         const int cr = crow(i, 0);
;                         float v = S[kt][i] * QK_C + bl[32 * kt + cr + 4 * hh - ql + 32];
;                         if (edge) { const int kidx = i0 - 64 + 32 * kt + cr + 4 * hh; if (kidx < 0 || kidx >= L) v = -1e30f; }
;                         S[kt][i] = v; mxp[i & 1] = fmaxf(mxp[i & 1], v);
;                     }
;                 float mx = fmaxf(mxp[0], mxp[1]);
;                 mx = fmaxf(mx, __shfl_xor(mx, 32));
.LmixA_fast:
	v_mul_f32_e32 v64, 0x3e38aa3b, v64
	v_mul_f32_e32 v167, 0x3e38aa3b, v65
	v_mul_f32_e32 v66, 0x3e38aa3b, v66
	v_mov_b32_e32 v65, v167
	v_mul_f32_e32 v169, 0x3e38aa3b, v67
	v_mov_b32_e32 v67, v169
	s_mov_b32 s22, 0xf149f2ca
	v_mul_f32_e32 v68, 0x3e38aa3b, v68
	v_max3_f32 v171, v65, s22, v67
	v_mul_f32_e32 v167, 0x3e38aa3b, v69
	v_mul_f32_e32 v70, 0x3e38aa3b, v70
	v_mov_b32_e32 v69, v167
	v_mul_f32_e32 v169, 0x3e38aa3b, v71
	v_mov_b32_e32 v71, v169
	v_mul_f32_e32 v72, 0x3e38aa3b, v72
	v_mul_f32_e32 v167, 0x3e38aa3b, v73
	v_mul_f32_e32 v74, 0x3e38aa3b, v74
	v_mov_b32_e32 v73, v167
	v_mul_f32_e32 v169, 0x3e38aa3b, v75
	v_mov_b32_e32 v168, v169
	v_mul_f32_e32 v75, 0x3e38aa3b, v76
	v_max_f32_e32 v170, 0xf149f2ca, v64
	v_max3_f32 v170, v170, v66, v68
	v_max3_f32 v171, v171, v69, v71
	v_max3_f32 v170, v170, v70, v72
	v_max3_f32 v169, v171, v73, v168
	v_max3_f32 v172, v170, v74, v75
	v_mul_f32_e32 v167, 0x3e38aa3b, v77
	v_mov_b32_e32 v76, v167
	v_mul_f32_e32 v77, 0x3e38aa3b, v78
	v_mul_f32_e32 v171, 0x3e38aa3b, v79
	v_mul_f32_e32 v48, 0x3e38aa3b, v48
	v_mov_b32_e32 v78, v171
	v_mul_f32_e32 v167, 0x3e38aa3b, v49
	v_mul_f32_e32 v50, 0x3e38aa3b, v50
	v_mov_b32_e32 v49, v167
	v_mul_f32_e32 v171, 0x3e38aa3b, v51
	v_mov_b32_e32 v51, v171
	v_mul_f32_e32 v52, 0x3e38aa3b, v52
	v_mul_f32_e32 v167, 0x3e38aa3b, v53
	v_mul_f32_e32 v54, 0x3e38aa3b, v54
	v_mov_b32_e32 v53, v167
	v_mul_f32_e32 v171, 0x3e38aa3b, v55
	v_mov_b32_e32 v55, v171
	v_mul_f32_e32 v56, 0x3e38aa3b, v56
	v_mul_f32_e32 v167, 0x3e38aa3b, v57
	v_mul_f32_e32 v58, 0x3e38aa3b, v58
	v_mov_b32_e32 v57, v167
	v_mul_f32_e32 v171, 0x3e38aa3b, v59
	v_mov_b32_e32 v59, v171
	v_mul_f32_e32 v60, 0x3e38aa3b, v60
	v_mul_f32_e32 v167, 0x3e38aa3b, v61
	v_mov_b32_e32 v61, v167
	v_max3_f32 v79, v169, v76, v78
	v_max3_f32 v169, v172, v77, v48
	v_max3_f32 v169, v169, v50, v52
	v_mul_f32_e32 v62, 0x3e38aa3b, v62
	v_max3_f32 v169, v169, v54, v56
	v_max3_f32 v166, v169, v58, v60
	v_mov_b32_e32 v169, v62
	v_mul_f32_e32 v171, 0x3e38aa3b, v63
	v_mov_b32_e32 v208, v171
	v_max3_f32 v79, v79, v49, v51
	v_mul_f32_e32 v32, 0x3e38aa3b, v32
	v_mov_b32_e32 v209, v32
	v_max3_f32 v32, v166, v169, v209
	v_mul_f32_e32 v63, 0x3e38aa3b, v33
	v_mov_b32_e32 v210, v63
	v_mul_f32_e32 v33, 0x3e38aa3b, v34
	v_mul_f32_e32 v167, 0x3e38aa3b, v35
	v_mul_f32_e32 v35, 0x3e38aa3b, v36
	v_mov_b32_e32 v34, v167
	v_mul_f32_e32 v63, 0x3e38aa3b, v37
	v_mov_b32_e32 v36, v63
	v_mul_f32_e32 v37, 0x3e38aa3b, v38
	v_mul_f32_e32 v167, 0x3e38aa3b, v39
	v_mul_f32_e32 v39, 0x3e38aa3b, v40
	v_mov_b32_e32 v38, v167
	v_mul_f32_e32 v63, 0x3e38aa3b, v41
	v_mov_b32_e32 v40, v63
	v_mul_f32_e32 v41, 0x3e38aa3b, v42
	v_mul_f32_e32 v167, 0x3e38aa3b, v43
	v_mul_f32_e32 v43, 0x3e38aa3b, v44
	v_mov_b32_e32 v42, v167
	v_mul_f32_e32 v63, 0x3e38aa3b, v45
	v_mov_b32_e32 v44, v63
	v_mul_f32_e32 v45, 0x3e38aa3b, v46
	v_mul_f32_e32 v167, 0x3e38aa3b, v47
	v_mul_f32_e32 v16, 0x3e38aa3b, v16
	v_mov_b32_e32 v46, v167
	v_mul_f32_e32 v63, 0x3e38aa3b, v17
	v_max3_f32 v79, v79, v53, v55
	v_max3_f32 v79, v79, v57, v59
	v_max3_f32 v79, v79, v61, v208
	v_mul_f32_e32 v18, 0x3e38aa3b, v18
	v_mul_f32_e32 v167, 0x3e38aa3b, v19
	v_max3_f32 v79, v79, v210, v34
	v_max3_f32 v79, v79, v36, v38
	v_mov_b32_e32 v17, v63
	v_max3_f32 v79, v79, v40, v42
	v_max3_f32 v47, v79, v44, v46
	v_mov_b32_e32 v19, v167
	v_max3_f32 v79, v47, v17, v19
	v_mul_f32_e32 v20, 0x3e38aa3b, v20
	v_mul_f32_e32 v63, 0x3e38aa3b, v21
	v_mov_b32_e32 v47, v63
	v_mul_f32_e32 v21, 0x3e38aa3b, v22
	v_mov_b32_e32 v211, v21
	v_mul_f32_e32 v167, 0x3e38aa3b, v23
	v_mov_b32_e32 v23, v167
	v_mul_f32_e32 v22, 0x3e38aa3b, v24
	v_mul_f32_e32 v63, 0x3e38aa3b, v25
	v_mul_f32_e32 v25, 0x3e38aa3b, v26
	v_mov_b32_e32 v24, v63
	v_mul_f32_e32 v167, 0x3e38aa3b, v27
	v_max3_f32 v21, v79, v47, v23
	v_mov_b32_e32 v27, v167
	v_max3_f32 v79, v21, v24, v27
	v_mul_f32_e32 v21, 0x3e38aa3b, v28
	v_mul_f32_e32 v63, 0x3e38aa3b, v29
	v_mul_f32_e32 v28, 0x3e38aa3b, v30
	v_mul_f32_e32 v29, 0x3e38aa3b, v31
	v_max3_f32 v32, v32, v33, v35
	v_max3_f32 v32, v32, v37, v39
	v_mul_f32_e32 v0, 0x3e38aa3b, v0
	v_max3_f32 v32, v32, v41, v43
	v_max3_f32 v32, v32, v45, v16
	v_max3_f32 v32, v32, v18, v20
	v_mov_b32_e32 v223, v0
	v_mul_f32_e32 v31, 0x3e38aa3b, v1
	v_max3_f32 v32, v32, v211, v22
	v_max3_f32 v32, v32, v25, v21
	v_max3_f32 v30, v32, v28, v223
	v_mul_f32_e32 v0, 0x3e38aa3b, v2
	v_mov_b32_e32 v225, v0
	v_mul_f32_e32 v1, 0x3e38aa3b, v3
	v_mov_b32_e32 v227, v1
	v_mul_f32_e32 v0, 0x3e38aa3b, v4
	v_mov_b32_e32 v228, v0
	v_mul_f32_e32 v3, 0x3e38aa3b, v5
	v_mov_b32_e32 v230, v3
	v_mul_f32_e32 v0, 0x3e38aa3b, v6
	v_mov_b32_e32 v232, v0
	v_mul_f32_e32 v1, 0x3e38aa3b, v7
	v_mov_b32_e32 v233, v1
	v_mul_f32_e32 v0, 0x3e38aa3b, v8
	v_mov_b32_e32 v231, v0
	v_mul_f32_e32 v3, 0x3e38aa3b, v9
	v_mov_b32_e32 v234, v3
	v_mul_f32_e32 v0, 0x3e38aa3b, v10
	v_mov_b32_e32 v235, v0
	v_mul_f32_e32 v1, 0x3e38aa3b, v11
	v_mov_b32_e32 v236, v1
	v_mul_f32_e32 v0, 0x3e38aa3b, v12
	v_max3_f32 v4, v30, v225, v228
	v_max3_f32 v4, v4, v232, v231
	v_mov_b32_e32 v237, v0
	v_max3_f32 v2, v4, v235, v237
	v_mul_f32_e32 v3, 0x3e38aa3b, v13
	v_mov_b32_e32 v240, v3
	v_mul_f32_e32 v0, 0x3e38aa3b, v14
	v_mov_b32_e32 v26, v63
	v_mov_b32_e32 v224, v29
	v_mov_b32_e32 v239, v0
	v_max3_f32 v29, v79, v26, v224
	v_mov_b32_e32 v226, v31
	v_max3_f32 v29, v29, v226, v227
	v_mul_f32_e32 v1, 0x3e38aa3b, v15
	v_max3_f32 v5, v29, v230, v233
	v_max3_f32 v5, v5, v234, v236
	v_mov_b32_e32 v241, v1
	v_max3_f32 v0, v5, v240, v241
	v_max3_f32 v0, v2, v239, v0
